# stack6 + attention warm start without the compiler's vmcnt(0) waits (previous unit's output stores keep draining)
# baseline (speedup 1.0000x reference)
; #define LAS __attribute__((address_space(3)))
; template <int THRL, bool FIXM> __device__ __forceinline__ bool attn_unit(const h16* Qrows, const h16* __restrict__ Kh, const h16* __restrict__ Vh, const int NT, h16* Yrows, const h16* BZrows, char* shm, const int tid, const float mfix, ...
;     ...
;   else { asm volatile("s_waitcnt vmcnt(4) lgkmcnt(0)\n\ts_barrier" ::: "memory");
; #pragma unroll
;       for (int d0 = 0; d0 < 4; ++d0) qr[d0] = *(const LAS s16x8*)((lds_cptr)shm + LDS_QN + wid * 4096 + (2 * d0 + hi) * 512 + r32 * 16); }
;   qkt(pA0, pA1, Kbase, qr, negm, r32, hi); asm volatile("s_nop 15\n\ts_nop 7" : "+v"(pA0), "+v"(pA1));
;   START(pA0, pA1);
.LBB0_69:
	s_andn2_b64 vcc, exec, s[2:3]
	v_lshlrev_b32_e32 v0, 4, v250
	s_cbranch_vccnz .LBB0_71
	s_lshl_b32 s2, s16, 12
	s_add_i32 s2, s41, s2
	s_add_i32 s2, s2, 0x16000
	v_lshlrev_b32_e32 v18, 9, v248
	s_waitcnt vmcnt(4) lgkmcnt(0)
	s_barrier
	v_add3_u32 v18, s2, v18, v0
	s_nop 0
	ds_read_b128 v[144:147], v18
	ds_read_b128 v[140:143], v18 offset:1024
	ds_read_b128 v[136:139], v18 offset:2048
	ds_read_b128 v[132:135], v18 offset:3072
	v_lshlrev_b32_e32 v18, 10, v248
	v_add3_u32 v219, s41, v18, v0
	ds_read_b128 v[38:41], v219
	v_mov_b32_e32 v53, s67
	s_nop 0
	v_add_f32_e32 v54, v1, v53
	s_and_b64 vcc, exec, s[0:1]
	s_mov_b64 s[2:3], -1
	s_waitcnt lgkmcnt(0)
	s_branch .Lat_warm_join

; __device__ __forceinline__ void qkt(f32x16& p0, f32x16& p1, const char* Kslot, const s16x8* qr, const f32x16& negm, int r32, int hi) {
;   const char* kb = Kslot + hi * 1024 + r32 * 16;
; #pragma unroll
;   for (int d0 = 0; d0 < 4; ++d0) {
;     const s16x8 b0 = *reinterpret_cast<const s16x8*>(kb + d0 * 2048);
;     const s16x8 b1 = *reinterpret_cast<const s16x8*>(kb + d0 * 2048 + 512);
;     if (d0 == 0) { p0 = __builtin_amdgcn_mfma_f32_32x32x16_f16(H8(b0), H8(qr[0]), negm, 0, 0, 0); p1 = __builtin_amdgcn_mfma_f32_32x32x16_f16(H8(b1), H8(qr[0]), negm, 0, 0, 0); }
;     else { p0 = __builtin_amdgcn_mfma_f32_32x32x16_f16(H8(b0), H8(qr[d0]), p0, 0, 0, 0); p1 = __builtin_amdgcn_mfma_f32_32x32x16_f16(H8(b1), H8(qr[d0]), p1, 0, 0, 0); } }
; }
.Lat_warm_join:
	v_mfma_f32_32x32x16_f16 v[18:33], v[38:41], v[144:147], v[2:17]
	ds_read_b128 v[38:41], v219 offset:512
	s_waitcnt lgkmcnt(0)
	v_mfma_f32_32x32x16_f16 v[2:17], v[38:41], v[144:147], v[2:17]
	ds_read_b128 v[38:41], v219 offset:2048
	s_waitcnt lgkmcnt(0)
	v_mfma_f32_32x32x16_f16 v[18:33], v[38:41], v[140:143], v[18:33]
	ds_read_b128 v[38:41], v219 offset:2560
	s_waitcnt lgkmcnt(0)
	v_mfma_f32_32x32x16_f16 v[2:17], v[38:41], v[140:143], v[2:17]
	ds_read_b128 v[38:41], v219 offset:4096
	s_waitcnt lgkmcnt(0)
	v_mfma_f32_32x32x16_f16 v[18:33], v[38:41], v[136:139], v[18:33]
	ds_read_b128 v[38:41], v219 offset:4608
	s_waitcnt lgkmcnt(0)
	v_mfma_f32_32x32x16_f16 v[2:17], v[38:41], v[136:139], v[2:17]
	ds_read_b128 v[38:41], v219 offset:6144
	s_waitcnt lgkmcnt(0)
	v_mfma_f32_32x32x16_f16 v[18:33], v[38:41], v[132:135], v[18:33]
	ds_read_b128 v[38:41], v219 offset:6656
	s_waitcnt lgkmcnt(0)
	v_mfma_f32_32x32x16_f16 v[2:17], v[38:41], v[132:135], v[2:17]
	s_nop 15
	s_nop 7
	s_nop 0
	v_sub_f32_e32 v0, v2, v53
	s_nop 10
	v_xor_b32_e32 v2, 0x80000000, v54
	v_sub_f32_e32 v38, v18, v53
	v_sub_f32_e32 v39, v19, v53
	v_sub_f32_e32 v18, v3, v53
	v_sub_f32_e32 v40, v20, v53
	v_sub_f32_e32 v19, v4, v53
	v_sub_f32_e32 v41, v21, v53
	v_sub_f32_e32 v20, v5, v53
	v_sub_f32_e32 v42, v22, v53
	v_sub_f32_e32 v21, v6, v53
	v_sub_f32_e32 v43, v23, v53
	v_sub_f32_e32 v22, v7, v53
	v_sub_f32_e32 v44, v24, v53
	v_sub_f32_e32 v23, v8, v53
	v_sub_f32_e32 v45, v25, v53
	v_sub_f32_e32 v24, v9, v53
	v_sub_f32_e32 v46, v26, v53
	v_sub_f32_e32 v25, v10, v53
	v_sub_f32_e32 v47, v27, v53
	v_sub_f32_e32 v26, v11, v53
	v_sub_f32_e32 v48, v28, v53
	v_sub_f32_e32 v27, v12, v53
	v_sub_f32_e32 v49, v29, v53
	v_sub_f32_e32 v28, v13, v53
	v_sub_f32_e32 v50, v30, v53
	v_sub_f32_e32 v29, v14, v53
	v_sub_f32_e32 v51, v31, v53
	v_sub_f32_e32 v30, v15, v53
	v_sub_f32_e32 v52, v32, v53
	v_sub_f32_e32 v31, v16, v53
	v_sub_f32_e32 v32, v17, v53
	v_mov_b32_e32 v3, v2
	v_mov_b32_e32 v4, v2
	v_mov_b32_e32 v5, v2
	v_mov_b32_e32 v6, v2
	v_mov_b32_e32 v7, v2
	v_mov_b32_e32 v8, v2
	v_mov_b32_e32 v9, v2
	v_mov_b32_e32 v10, v2
	v_mov_b32_e32 v11, v2
	v_mov_b32_e32 v12, v2
	v_mov_b32_e32 v13, v2
	v_mov_b32_e32 v14, v2
	v_mov_b32_e32 v15, v2
	v_mov_b32_e32 v16, v2
	v_mov_b32_e32 v17, v2
	v_sub_f32_e32 v33, v33, v53
	s_cbranch_vccnz .LBB0_73
	s_waitcnt vmcnt(0) lgkmcnt(0)
	s_barrier
	s_mov_b64 s[2:3], 0
